# LRU segment heads: counted vmcnt (8 / 4) so the raw-row LDS write does not wait for the previous segment's LSUM / RNN stores; pass-1 prologue drains its raw loads once
# speedup vs baseline: 1.0021x; 1.0021x over previous
; __device__ __forceinline__ unsigned pk2(float lo, float hi) { return pg8::cvt_pk_bf16(lo, hi); }
; template <int PASS> __device__ __forceinline__ void phase_lru(LAS unsigned char* lds, const bf16_t* Z, const bf16_t* WL, float* LSUM, const float* LCAR, bf16_t* RNN,
;                                                               int S, int tid, int lane, int wave, int G) {
;     ...
;             if (PASS == 1) {
; #pragma unroll
;                 for (int t = 0; t < 4; ++t) ryr[t] = *(const u32x2*)(Z + (size_t)(t0 + 16 * t + c) * DIN + C_RY + ch0);
;                 car[0] = *(const f32x4*)(LCAR + (size_t)(seg * 2 + 0) * LW + ch0); car[1] = *(const f32x4*)(LCAR + (size_t)(seg * 2 + 1) * LW + ch0);
;             }
;     ...
;                     if (PASS == 1) { u32x2 w; w.x = pk2(ov[0], ov[1]); w.y = pk2(ov[2], ov[3]); *(u32x2*)(RNN + (size_t)(t0 + 16 * t + c) * LW + ch0) = w; }
.LBB0_180:
	s_or_b64 exec, exec, s[0:1]
	s_bfe_u32 s0, s19, 0x60002
	s_lshl_b32 s1, s0, 8
	v_or_b32_e32 v1, s1, v208
	v_mul_u32_u24_e32 v84, 0xc00, v1
	v_or_b32_e32 v1, s1, v209
	s_mul_i32 s34, s0, 0x60000
	v_mul_u32_u24_e32 v86, 0xc00, v1
	v_or_b32_e32 v1, s34, v210
	v_lshlrev_b32_e32 v88, 1, v1
	v_add_u32_e32 v1, s1, v211
	v_add_u32_e32 v94, s1, v212
	v_add_u32_e32 v95, s1, v213
	s_or_b32 s28, s1, 64
	v_or_b32_e32 v2, s34, v214
	s_mul_i32 s1, s0, 0x2e0000
	v_lshlrev_b32_e32 v90, 1, v2
	v_add_lshl_u32 v92, v215, s1, 1
	v_mad_u64_u32 v[2:3], s[0:1], s0, v197, v[82:83]
	v_lshlrev_b64 v[80:81], 1, v[80:81]
	s_mov_b64 s[0:1], 0xdd00000
	v_mov_b32_e32 v85, v0
	v_lshl_add_u64 v[82:83], v[80:81], 0, s[0:1]
	v_lshl_add_u64 v[114:115], v[82:83], 0, v[84:85]
	v_mad_i64_i32 v[84:85], s[0:1], v1, s27, v[112:113]
	s_lshl_b64 s[0:1], s[58:59], 1
	s_nop 0
	v_lshl_add_u64 v[120:121], v[84:85], 0, s[0:1]
	v_mad_i64_i32 v[84:85], s[46:47], v94, s27, v[112:113]
	v_mov_b32_e32 v87, v0
	v_mov_b32_e32 v89, v0
	v_mov_b32_e32 v91, v0
	v_mov_b32_e32 v93, v0
	v_lshl_add_u64 v[122:123], v[84:85], 0, s[0:1]
	v_mad_i64_i32 v[84:85], s[46:47], v95, s27, v[112:113]
	v_lshl_add_u64 v[116:117], v[82:83], 0, v[86:87]
	v_lshl_add_u64 v[118:119], v[82:83], 0, v[88:89]
	v_lshl_add_u64 v[124:125], v[84:85], 0, s[0:1]
	v_lshl_add_u64 v[126:127], v[82:83], 0, v[90:91]
	v_lshl_add_u64 v[128:129], v[80:81], 0, v[92:93]
	s_mov_b32 s34, 0
	s_waitcnt vmcnt(0)
	s_branch .LBB0_183

; #define LAS __attribute__((address_space(3)))
; template <int PASS> __device__ __forceinline__ void phase_lru(LAS unsigned char* lds, const bf16_t* Z, const bf16_t* WL, float* LSUM, const float* LCAR, bf16_t* RNN,
;                                                               int S, int tid, int lane, int wave, int G) {
;     ...
; #pragma unroll
;             for (int i = 0; i < 3; ++i) { const int idx = tid + 512 * i; if (idx < 67 * 16) *(LAS u32x4*)(lds + LRU_RAW + (idx >> 4) * LRU_RAWP + 16 * (idx & 15)) = rawr[i]; }
.LBB0_186:
	s_waitcnt vmcnt(4)
	ds_write_b128 v218, v[76:79]

; #define LAS __attribute__((address_space(3)))
; template <int PASS> __device__ __forceinline__ void phase_lru(LAS unsigned char* lds, const bf16_t* Z, const bf16_t* WL, float* LSUM, const float* LCAR, bf16_t* RNN,
;                                                               int S, int tid, int lane, int wave, int G) {
;     ...
; #pragma unroll
;             for (int i = 0; i < 3; ++i) { const int idx = tid + 512 * i; if (idx < 67 * 16) *(LAS u32x4*)(lds + LRU_RAW + (idx >> 4) * LRU_RAWP + 16 * (idx & 15)) = rawr[i]; }
.LBB0_194:
	s_waitcnt vmcnt(4)
	ds_write_b128 v216, v[68:71]
	s_or_b64 exec, exec, s[0:1]
	s_and_saveexec_b64 s[0:1], s[42:43]
	s_cbranch_execz .LBB0_185
.LBB0_195:
	s_waitcnt vmcnt(4)
	ds_write_b128 v217, v[72:75]
	s_or_b64 exec, exec, s[0:1]
	s_and_saveexec_b64 s[0:1], s[44:45]
	s_cbranch_execnz .LBB0_186
	s_branch .LBB0_187

; #define LAS __attribute__((address_space(3)))
; template <int PASS> __device__ __forceinline__ void phase_lru(LAS unsigned char* lds, const bf16_t* Z, const bf16_t* WL, float* LSUM, const float* LCAR, bf16_t* RNN,
;                                                               int S, int tid, int lane, int wave, int G) {
;     ...
; #pragma unroll
;             for (int i = 0; i < 3; ++i) { const int idx = tid + 512 * i; if (idx < 67 * 16) *(LAS u32x4*)(lds + LRU_RAW + (idx >> 4) * LRU_RAWP + 16 * (idx & 15)) = rawr[i]; }
.LBB0_224:
	s_waitcnt vmcnt(8)
	ds_write_b128 v164, v[76:79]

; #define LAS __attribute__((address_space(3)))
; template <int PASS> __device__ __forceinline__ void phase_lru(LAS unsigned char* lds, const bf16_t* Z, const bf16_t* WL, float* LSUM, const float* LCAR, bf16_t* RNN,
;                                                               int S, int tid, int lane, int wave, int G) {
;     ...
; #pragma unroll
;             for (int i = 0; i < 3; ++i) { const int idx = tid + 512 * i; if (idx < 67 * 16) *(LAS u32x4*)(lds + LRU_RAW + (idx >> 4) * LRU_RAWP + 16 * (idx & 15)) = rawr[i]; }
.LBB0_237:
	s_waitcnt vmcnt(8)
	ds_write_b128 v162, v[68:71]
	s_or_b64 exec, exec, s[18:19]
	s_and_saveexec_b64 s[18:19], s[44:45]
	s_cbranch_execz .LBB0_223
.LBB0_238:
	s_waitcnt vmcnt(8)
	ds_write_b128 v163, v[72:75]
	s_or_b64 exec, exec, s[18:19]
	s_and_saveexec_b64 s[18:19], s[46:47]
	s_cbranch_execnz .LBB0_224
	s_branch .LBB0_225
